# v62 + hgC loop: dynamic-queue draw (returning atomic) no longer waited at the item top; result collected behind the norm section's vmcnt(0) and read after the last barrier
# baseline (speedup 1.0000x reference)
; #define GAS __attribute__((address_space(1)))
; #define LAS __attribute__((address_space(3)))
; __device__ __forceinline__ unsigned pk2(float lo, float hi) { f32x2_t v = {lo, hi}; bf16x2_t h = __builtin_convertvector(v, bf16x2_t); return __builtin_bit_cast(unsigned, h); }
; __device__ __forceinline__ float siluf_(float x) { return x * __builtin_amdgcn_rcpf(1.0f + __builtin_amdgcn_exp2f(-1.4426950408889634f * x)); }
; __device__ __forceinline__ void hgC_loop(Frame& F, unsigned* ctr) {
;     ...
;         { float ss = 0.f;
; #pragma unroll
;           for (int r = 0; r < 16; ++r) ss += acc[r] * acc[r];
;           ss += __shfl_xor(ss, 32);
;           if (hh == 0) SS[t * 4 + vb] = ss; }
;         __syncthreads();
;         { const f32x4 s4 = *(const LAS f32x4*)(SS + t * 4); const float rstd = __builtin_amdgcn_rsqf(((s4.x + s4.y) + (s4.z + s4.w)) * (1.0f / HD) + EPS);
; #pragma unroll
;           for (int q = 0; q < 4; ++q) { const int v0 = 32 * vb + 8 * q + 4 * hh; const f32x4 gn = *(const GAS f32x4*)(F.in[17] + v0);
;               v2u w; w.x = pk2(acc[4 * q] * rstd * gn.x * siluf_(bflo(ogc[q].x)), acc[4 * q + 1] * rstd * gn.y * siluf_(bfhi(ogc[q].x)));
;               w.y = pk2(acc[4 * q + 2] * rstd * gn.z * siluf_(bflo(ogc[q].y)), acc[4 * q + 3] * rstd * gn.w * siluf_(bfhi(ogc[q].y)));
;               *(v2u*)(MIX + (size_t)(tok0 + t) * DM + 512 + h * HD + v0) = w; } }
;         __syncthreads();
.LBB0_692:
	s_or_b64 exec, exec, s[24:25]
	s_waitcnt lgkmcnt(0)
	s_barrier
	v_add_u32_e32 v75, 0, v93
	v_lshlrev_b32_e32 v104, 16, v80
	ds_read_b128 v[100:103], v75 offset:52224
	s_lshl_b32 s10, s18, 4
	s_lshl_b32 s13, s18, 6
	v_mul_f32_e32 v75, 0xbfb8aa3b, v104
	v_and_b32_e32 v105, 0xffff0000, v80
	s_and_b32 s24, s10, 0xfffff800
	s_and_b32 s13, s13, 0x7c0
	v_exp_f32_e32 v75, v75
	v_lshlrev_b32_e32 v80, 16, v81
	v_and_b32_e32 v81, 0xffff0000, v81
	v_mul_f32_e32 v106, 0xbfb8aa3b, v105
	s_or_b32 s13, s24, s13
	v_mul_f32_e32 v107, 0xbfb8aa3b, v80
	v_mul_f32_e32 v108, 0xbfb8aa3b, v81
	v_exp_f32_e32 v110, v106
	v_add_u32_e32 v106, s13, v90
	v_exp_f32_e32 v111, v107
	v_exp_f32_e32 v112, v108
	v_ashrrev_i32_e32 v107, 31, v106
	s_waitcnt lgkmcnt(0)
	v_mov_b32_e32 v108, v101
	v_mov_b32_e32 v109, v102
	v_mov_b32_e32 v101, v103
	s_lshl_b32 s18, s18, 3
	v_lshlrev_b64 v[106:107], 11, v[106:107]
	v_add_f32_e32 v75, 1.0, v75
	v_pk_add_f32 v[100:101], v[108:109], v[100:101]
	s_and_b32 s10, s18, 0x300
	v_lshl_add_u64 v[102:103], s[50:51], 0, v[106:107]
	v_rcp_f32_e32 v106, v75
	v_add_f32_e32 v75, v100, v101
	v_lshl_add_u64 v[102:103], v[102:103], 0, s[10:11]
	v_fmamk_f32 v75, v75, 0x3c000000, v98
	v_add_f32_e32 v107, 1.0, v110
	v_add_f32_e32 v110, 1.0, v111
	v_add_f32_e32 v111, 1.0, v112
	v_lshl_add_u64 v[100:101], v[102:103], 0, v[54:55]
	v_rsq_f32_e32 v102, v75
	v_rcp_f32_e32 v107, v107
	v_rcp_f32_e32 v108, v110
	v_rcp_f32_e32 v109, v111
	v_pk_mul_f32 v[2:3], v[2:3], v[102:103] op_sel_hi:[1,0]
	v_pk_mul_f32 v[4:5], v[4:5], v[102:103] op_sel_hi:[1,0]
	v_pk_mul_f32 v[104:105], v[106:107], v[104:105]
	v_pk_mul_f32 v[80:81], v[108:109], v[80:81]
	v_add_co_u32_e32 v110, vcc, s19, v100
	s_mov_b32 s18, s16
	s_nop 0
	v_addc_co_u32_e32 v111, vcc, 0, v101, vcc
	v_lshl_add_u64 v[100:101], v[100:101], 0, s[14:15]
	s_andn2_b64 vcc, exec, s[20:21]
	s_waitcnt vmcnt(0)
	s_and_saveexec_b64 s[28:29], s[92:93]
	s_cbranch_execz my_hgcq_b
	ds_write_b32 v55, v236 offset:53256
my_hgcq_b:
	s_or_b64 exec, exec, s[28:29]
	v_pk_mul_f32 v[2:3], v[198:199], v[2:3]
	v_pk_mul_f32 v[4:5], v[200:201], v[4:5]
	v_pk_mul_f32 v[2:3], v[104:105], v[2:3]
	v_pk_mul_f32 v[4:5], v[80:81], v[4:5]
	v_cvt_pk_bf16_f32 v2, v2, v3
	v_cvt_pk_bf16_f32 v3, v4, v5
	global_store_dwordx2 v[110:111], v[2:3], off offset:1024
	v_lshlrev_b32_e32 v50, 16, v78
	v_and_b32_e32 v51, 0xffff0000, v78
	v_lshlrev_b32_e32 v52, 16, v79
	v_and_b32_e32 v53, 0xffff0000, v79
	v_mul_f32_e32 v75, 0xbfb8aa3b, v50
	v_mul_f32_e32 v78, 0xbfb8aa3b, v51
	v_mul_f32_e32 v79, 0xbfb8aa3b, v52
	v_mul_f32_e32 v80, 0xbfb8aa3b, v53
	v_exp_f32_e32 v75, v75
	v_exp_f32_e32 v78, v78
	v_exp_f32_e32 v79, v79
	v_exp_f32_e32 v80, v80
	v_add_f32_e32 v75, 1.0, v75
	v_add_f32_e32 v81, 1.0, v78
	v_add_f32_e32 v103, 1.0, v79
	v_add_f32_e32 v104, 1.0, v80
	v_rcp_f32_e32 v78, v75
	v_rcp_f32_e32 v79, v81
	v_rcp_f32_e32 v80, v103
	v_rcp_f32_e32 v81, v104
	v_pk_mul_f32 v[6:7], v[6:7], v[102:103] op_sel_hi:[1,0]
	v_pk_mul_f32 v[8:9], v[8:9], v[102:103] op_sel_hi:[1,0]
	v_pk_mul_f32 v[50:51], v[78:79], v[50:51]
	v_pk_mul_f32 v[52:53], v[80:81], v[52:53]
	v_pk_mul_f32 v[10:11], v[10:11], v[102:103] op_sel_hi:[1,0]
	v_pk_mul_f32 v[12:13], v[12:13], v[102:103] op_sel_hi:[1,0]
	v_pk_mul_f32 v[14:15], v[14:15], v[102:103] op_sel_hi:[1,0]
	v_pk_mul_f32 v[16:17], v[16:17], v[102:103] op_sel_hi:[1,0]
	v_cndmask_b32_e64 v75, 0, 1, s[22:23]
	v_mov_b64_e32 v[78:79], v[84:85]
	v_mov_b64_e32 v[80:81], v[82:83]
	v_xor_b32_e32 v99, v99, v75
	v_pk_mul_f32 v[2:3], v[202:203], v[6:7]
	v_pk_mul_f32 v[4:5], v[204:205], v[8:9]
	v_pk_mul_f32 v[2:3], v[50:51], v[2:3]
	v_pk_mul_f32 v[4:5], v[52:53], v[4:5]
	v_cvt_pk_bf16_f32 v2, v2, v3
	v_cvt_pk_bf16_f32 v3, v4, v5
	global_store_dwordx2 v[100:101], v[2:3], off offset:16
	v_lshlrev_b32_e32 v6, 16, v76
	v_and_b32_e32 v7, 0xffff0000, v76
	v_lshlrev_b32_e32 v8, 16, v77
	v_and_b32_e32 v9, 0xffff0000, v77
	v_mul_f32_e32 v50, 0xbfb8aa3b, v6
	v_mul_f32_e32 v51, 0xbfb8aa3b, v7
	v_mul_f32_e32 v52, 0xbfb8aa3b, v8
	v_mul_f32_e32 v53, 0xbfb8aa3b, v9
	v_exp_f32_e32 v50, v50
	v_exp_f32_e32 v51, v51
	v_exp_f32_e32 v52, v52
	v_exp_f32_e32 v53, v53
	v_add_f32_e32 v50, 1.0, v50
	v_add_f32_e32 v51, 1.0, v51
	v_add_f32_e32 v52, 1.0, v52
	v_add_f32_e32 v53, 1.0, v53
	v_rcp_f32_e32 v50, v50
	v_rcp_f32_e32 v51, v51
	v_rcp_f32_e32 v52, v52
	v_rcp_f32_e32 v53, v53
	v_mov_b64_e32 v[76:77], v[86:87]
	v_pk_mul_f32 v[6:7], v[50:51], v[6:7]
	v_pk_mul_f32 v[8:9], v[52:53], v[8:9]
	v_mov_b64_e32 v[52:53], v[44:45]
	v_mov_b64_e32 v[50:51], v[42:43]
	v_pk_mul_f32 v[2:3], v[10:11], v[206:207]
	v_pk_mul_f32 v[4:5], v[12:13], v[208:209]
	v_pk_mul_f32 v[2:3], v[6:7], v[2:3]
	v_pk_mul_f32 v[4:5], v[8:9], v[4:5]
	v_cvt_pk_bf16_f32 v2, v2, v3
	v_cvt_pk_bf16_f32 v3, v4, v5
	global_store_dwordx2 v[100:101], v[2:3], off offset:32
	v_lshlrev_b32_e32 v10, 16, v70
	v_and_b32_e32 v11, 0xffff0000, v70
	v_lshlrev_b32_e32 v12, 16, v71
	v_and_b32_e32 v13, 0xffff0000, v71
	v_mul_f32_e32 v42, 0xbfb8aa3b, v10
	v_mul_f32_e32 v43, 0xbfb8aa3b, v11
	v_mul_f32_e32 v44, 0xbfb8aa3b, v12
	v_mul_f32_e32 v45, 0xbfb8aa3b, v13
	v_exp_f32_e32 v42, v42
	v_exp_f32_e32 v43, v43
	v_exp_f32_e32 v44, v44
	v_exp_f32_e32 v45, v45
	v_add_f32_e32 v42, 1.0, v42
	v_add_f32_e32 v43, 1.0, v43
	v_add_f32_e32 v44, 1.0, v44
	v_add_f32_e32 v45, 1.0, v45
	v_rcp_f32_e32 v42, v42
	v_rcp_f32_e32 v43, v43
	v_rcp_f32_e32 v44, v44
	v_rcp_f32_e32 v45, v45
	v_mov_b64_e32 v[6:7], v[46:47]
	v_pk_mul_f32 v[10:11], v[42:43], v[10:11]
	v_mov_b64_e32 v[70:71], v[88:89]
	v_pk_mul_f32 v[12:13], v[44:45], v[12:13]
	v_mov_b64_e32 v[8:9], v[48:49]
	v_pk_mul_f32 v[2:3], v[14:15], v[210:211]
	v_pk_mul_f32 v[4:5], v[16:17], v[212:213]
	v_pk_mul_f32 v[2:3], v[10:11], v[2:3]
	v_pk_mul_f32 v[4:5], v[12:13], v[4:5]
	v_cvt_pk_bf16_f32 v2, v2, v3
	v_cvt_pk_bf16_f32 v3, v4, v5
	global_store_dwordx2 v[100:101], v[2:3], off offset:48
	s_waitcnt lgkmcnt(0)
	s_barrier
	ds_read_b32 v237, v55 offset:53256
	s_waitcnt lgkmcnt(0)
	v_readfirstlane_b32 s17, v237
	s_nop 3
	s_cbranch_vccz .LBB0_701
; #define LAS __attribute__((address_space(3)))
; __device__ __forceinline__ void hgC_loop(Frame& F, unsigned* ctr) {
;     ...
;         const int bh = item >> 5, chunk = item & 31, b = bh >> 2, h = bh & 3, tok0 = b * PB_T + chunk * 64;
; #pragma unroll
;         for (int i = 0; i < 4; ++i) { const int p = tid + 512 * i; *(LAS v4u*)(SC + (p >> 4) * HG_LDQ + (p & 15) * 8) = sc[i]; }
; #pragma unroll
;         for (int i = 0; i < 2; ++i) { const int p = tid + 512 * i; *(LAS v4u*)(Qh + (p >> 4) * HG_LDQ + (p & 15) * 8) = qh[i]; }
;         f32x16 acc;
;         acc[0] = bflo(oi[0].x); acc[1] = bfhi(oi[0].x); acc[2] = bflo(oi[0].y); acc[3] = bfhi(oi[0].y); acc[4] = bflo(oi[0].z); acc[5] = bfhi(oi[0].z); acc[6] = bflo(oi[0].w); acc[7] = bfhi(oi[0].w);
;         acc[8] = bflo(oi[1].x); acc[9] = bfhi(oi[1].x); acc[10] = bflo(oi[1].y); acc[11] = bfhi(oi[1].y); acc[12] = bflo(oi[1].z); acc[13] = bfhi(oi[1].z); acc[14] = bflo(oi[1].w); acc[15] = bfhi(oi[1].w);
;         v2u ogc[4];
; #pragma unroll
;         for (int q = 0; q < 4; ++q) ogc[q] = og[q];
;         if (tid == 0) slot[par] = (int)__hip_atomic_fetch_add(ctr, 1u, __ATOMIC_RELAXED, __HIP_MEMORY_SCOPE_AGENT);
;         if (nxt < 1024) HGC_FETCH(nxt);
;         __syncthreads();
;         const int nn = slot[par];
; #pragma unroll
;         for (int ks = 0; ks < 8; ++ks) { const s16x8 a = *(const LAS s16x8*)(SC + (32 * vb + r32) * HG_LDQ + 16 * ks + 8 * hh); const s16x8 bb = *(const LAS s16x8*)(Qh + t * HG_LDQ + 16 * ks + 8 * hh);
;             acc = __builtin_amdgcn_mfma_f32_32x32x16_bf16(a, bb, acc, 0, 0, 0); }
.LBB0_693:
	s_mov_b32 s16, s17
	s_waitcnt vmcnt(11)
	ds_write_b128 v94, v[18:21]
	s_waitcnt vmcnt(10)
	ds_write_b128 v95, v[22:25]
	s_waitcnt vmcnt(9)
	ds_write_b128 v94, v[26:29] offset:17408
	s_waitcnt vmcnt(8)
	ds_write_b128 v96, v[30:33]
	s_waitcnt vmcnt(7)
	ds_write_b128 v94, v[34:37] offset:34816
	s_waitcnt vmcnt(6)
	ds_write_b128 v95, v[38:41] offset:34816
	s_cmpk_lt_i32 s16, 0x400
	s_cselect_b64 s[22:23], -1, 0
	s_cmpk_gt_i32 s16, 0x3ff
	s_cselect_b64 s[20:21], -1, 0
	s_waitcnt vmcnt(4)
	v_mov_b64_e32 v[48:49], v[8:9]
	v_mov_b64_e32 v[42:43], v[50:51]
	s_and_b64 vcc, exec, s[20:21]
	s_waitcnt vmcnt(0)
	v_mov_b64_e32 v[88:89], v[70:71]
	v_mov_b64_e32 v[86:87], v[76:77]
	v_mov_b64_e32 v[84:85], v[78:79]
	v_mov_b64_e32 v[82:83], v[80:81]
	v_mov_b64_e32 v[46:47], v[6:7]
	v_mov_b64_e32 v[44:45], v[52:53]
	s_and_saveexec_b64 s[28:29], s[92:93]
	s_cbranch_execz my_hgcq_a
	v_mov_b32_e32 v237, 1
	global_atomic_add v236, v55, v237, s[4:5] sc0
my_hgcq_a:
	s_or_b64 exec, exec, s[28:29]
	s_cbranch_vccnz .LBB0_699
	s_ashr_i32 s17, s16, 31
	s_lshl_b64 s[24:25], s[16:17], 15
	v_lshl_add_u64 v[2:3], v[64:65], 0, s[24:25]
	v_lshl_add_u64 v[4:5], v[2:3], 0, v[56:57]
	s_lshl_b64 s[26:27], s[16:17], 14
	v_lshl_add_u64 v[10:11], v[2:3], 0, v[58:59]
	global_load_dwordx4 v[18:21], v[4:5], off
	global_load_dwordx4 v[22:25], v[10:11], off
	v_lshl_add_u64 v[4:5], v[2:3], 0, v[60:61]
	v_lshl_add_u64 v[2:3], v[2:3], 0, v[62:63]
	s_lshl_b32 s10, s16, 4
	s_lshl_b32 s13, s16, 6
	global_load_dwordx4 v[26:29], v[4:5], off
	global_load_dwordx4 v[30:33], v[2:3], off
	v_lshl_add_u64 v[2:3], v[66:67], 0, s[26:27]
	s_and_b32 s10, s10, 0xfffff800
	v_lshl_add_u64 v[4:5], v[2:3], 0, v[56:57]
	v_lshl_add_u64 v[2:3], v[2:3], 0, v[58:59]
	s_and_b32 s13, s13, 0x7c0
	global_load_dwordx4 v[34:37], v[4:5], off
	global_load_dwordx4 v[38:41], v[2:3], off
	v_lshl_add_u64 v[2:3], v[68:69], 0, s[26:27]
	s_or_b32 s10, s10, s13
	global_load_dwordx4 v[42:45], v[2:3], off offset:16
	global_load_dwordx4 v[46:49], v[2:3], off
	v_add_u32_e32 v2, s10, v90
	v_ashrrev_i32_e32 v3, 31, v2
	v_lshlrev_b64 v[2:3], 12, v[2:3]
	s_lshl_b32 s10, s16, 3
	v_lshl_add_u64 v[2:3], s[56:57], 0, v[2:3]
	s_and_b32 s10, s10, 0x300
	v_lshl_add_u64 v[2:3], v[2:3], 0, s[10:11]
	s_mov_b32 s13, s11
	v_lshl_add_u64 v[2:3], v[2:3], 0, s[12:13]
	v_mov_b32_e32 v75, v55
	v_lshl_add_u64 v[2:3], v[2:3], 0, v[74:75]
	global_load_dwordx2 v[82:83], v[2:3], off offset:3072
	global_load_dwordx2 v[84:85], v[2:3], off offset:3088
	global_load_dwordx2 v[86:87], v[2:3], off offset:3104
	global_load_dwordx2 v[88:89], v[2:3], off offset:3120
.LBB0_699:
	v_lshlrev_b32_e32 v13, 2, v99
	v_add_u32_e32 v13, 0, v13
	s_waitcnt lgkmcnt(0)
	s_barrier
	ds_read_b32 v75, v13 offset:53248
	ds_read_b128 v[100:103], v91
	ds_read_b128 v[104:107], v92 offset:34816
	v_lshlrev_b32_e32 v2, 16, v6
	v_and_b32_e32 v3, 0xffff0000, v6
	v_lshlrev_b32_e32 v4, 16, v7
	v_and_b32_e32 v5, 0xffff0000, v7
	v_lshlrev_b32_e32 v6, 16, v8
	v_and_b32_e32 v7, 0xffff0000, v8
	v_lshlrev_b32_e32 v8, 16, v9
	v_and_b32_e32 v9, 0xffff0000, v9
	v_lshlrev_b32_e32 v10, 16, v50
	v_and_b32_e32 v11, 0xffff0000, v50
	v_lshlrev_b32_e32 v12, 16, v51
	v_and_b32_e32 v13, 0xffff0000, v51
	v_lshlrev_b32_e32 v14, 16, v52
	v_and_b32_e32 v15, 0xffff0000, v52
	v_lshlrev_b32_e32 v16, 16, v53
	v_and_b32_e32 v17, 0xffff0000, v53
	ds_read_b128 v[50:53], v91 offset:32
	ds_read_b128 v[108:111], v92 offset:34848
	s_waitcnt lgkmcnt(2)
	v_mfma_f32_32x32x16_bf16 v[2:17], v[100:103], v[104:107], v[2:17]
	s_waitcnt lgkmcnt(0)
	v_mfma_f32_32x32x16_bf16 v[2:17], v[50:53], v[108:111], v[2:17]
	ds_read_b128 v[50:53], v91 offset:64
	ds_read_b128 v[100:103], v92 offset:34880
	ds_read_b128 v[104:107], v91 offset:96
	ds_read_b128 v[108:111], v92 offset:34912
	s_waitcnt lgkmcnt(2)
	v_mfma_f32_32x32x16_bf16 v[2:17], v[50:53], v[100:103], v[2:17]
	s_waitcnt lgkmcnt(0)
	v_mfma_f32_32x32x16_bf16 v[2:17], v[104:107], v[108:111], v[2:17]
	ds_read_b128 v[50:53], v91 offset:128
	ds_read_b128 v[100:103], v92 offset:34944
	ds_read_b128 v[104:107], v91 offset:160
	ds_read_b128 v[108:111], v92 offset:34976
	s_waitcnt lgkmcnt(2)
	v_mfma_f32_32x32x16_bf16 v[2:17], v[50:53], v[100:103], v[2:17]
	s_waitcnt lgkmcnt(0)
	v_mfma_f32_32x32x16_bf16 v[2:17], v[104:107], v[108:111], v[2:17]
	ds_read_b128 v[50:53], v91 offset:192
	ds_read_b128 v[100:103], v92 offset:35008
	ds_read_b128 v[104:107], v91 offset:224
	ds_read_b128 v[108:111], v92 offset:35040
	s_waitcnt lgkmcnt(2)
	v_mfma_f32_32x32x16_bf16 v[2:17], v[50:53], v[100:103], v[2:17]
	v_and_b32_e32 v51, 64, v97
	v_xor_b32_e32 v50, 32, v97
	v_add_u32_e32 v51, 64, v51
	v_cmp_lt_i32_e32 vcc, v50, v51
	s_nop 1
	v_cndmask_b32_e32 v51, v97, v50, vcc
	s_waitcnt lgkmcnt(0)
	v_mfma_f32_32x32x16_bf16 v[2:17], v[104:107], v[108:111], v[2:17]
	v_lshlrev_b32_e32 v51, 2, v51
	s_nop 10
	v_mul_f32_e32 v50, v3, v3
	v_fmac_f32_e32 v50, v2, v2
	v_fmac_f32_e32 v50, v4, v4
	v_fmac_f32_e32 v50, v5, v5
	v_fmac_f32_e32 v50, v6, v6
	v_fmac_f32_e32 v50, v7, v7
	v_fmac_f32_e32 v50, v8, v8
	v_fmac_f32_e32 v50, v9, v9
	v_fmac_f32_e32 v50, v10, v10
	v_fmac_f32_e32 v50, v11, v11
	v_fmac_f32_e32 v50, v12, v12
	v_fmac_f32_e32 v50, v13, v13
	v_fmac_f32_e32 v50, v14, v14
	v_fmac_f32_e32 v50, v15, v15
	v_fmac_f32_e32 v50, v16, v16
	v_fmac_f32_e32 v50, v17, v17
	ds_bpermute_b32 v51, v51, v50
	s_and_saveexec_b64 s[24:25], s[0:1]
	s_cbranch_execz .LBB0_692
	s_waitcnt lgkmcnt(0)
	v_add_f32_e32 v50, v50, v51
	v_add_u32_e32 v51, s3, v93
	ds_write_b32 v51, v50 offset:52224
	s_branch .LBB0_692
